# v036 + x->bf16 conversion loop loads issued together + split-KV combine: all 16 partial-O quads and partial sums loaded up front instead of 16 serialized round trips
# speedup vs baseline: 1.0118x; 1.0113x over previous
.LBB0_11:
	v_cmp_lt_i32_e64 s[6:7], s14, v16
	v_mov_b64_e32 v[18:19], v[16:17]
	v_mov_b64_e32 v[20:21], v[12:13]
	s_and_saveexec_b64 s[66:67], s[6:7]
	v_add_u32_e32 v4, 0xffffc000, v16
	v_lshlrev_b64 v[18:19], 12, v[4:5]
	v_mov_b32_e32 v4, v16
	v_lshl_add_u64 v[20:21], s[10:11], 0, v[18:19]
	v_mov_b64_e32 v[18:19], v[4:5]
	s_or_b64 exec, exec, s[66:67]
	v_lshl_add_u64 v[32:33], v[20:21], 0, v[14:15]
	global_load_dwordx4 v[20:23], v[32:33], off
	global_load_dwordx4 v[24:27], v[32:33], off offset:16
	v_lshlrev_b64 v[28:29], 11, v[18:19]
	v_lshl_add_u64 v[36:37], v[10:11], 0, v[28:29]
	global_load_dwordx4 v[28:31], v[32:33], off offset:2048
	s_nop 0
	global_load_dwordx4 v[32:35], v[32:33], off offset:2064
	s_waitcnt vmcnt(3)
	v_cvt_pk_bf16_f32 v38, v20, v21
	v_cvt_pk_bf16_f32 v39, v22, v23
	s_waitcnt vmcnt(2)
	v_cvt_pk_bf16_f32 v40, v24, v25
	v_cvt_pk_bf16_f32 v41, v26, v27
	global_store_dwordx4 v[36:37], v[38:41], off
	v_mul_f32_e32 v1, v21, v21
	v_mul_f32_e32 v4, v23, v23
	v_mul_f32_e32 v21, v25, v25
	v_mul_f32_e32 v23, v27, v27
	v_fmac_f32_e32 v1, v20, v20
	v_fmac_f32_e32 v4, v22, v22
	v_fmac_f32_e32 v21, v24, v24
	v_fmac_f32_e32 v23, v26, v26
	v_add_f32_e32 v1, v1, v4
	v_add_f32_e32 v4, v21, v23
	v_add_f32_e32 v1, v1, v4
	s_waitcnt vmcnt(2)
	v_mul_f32_e32 v4, v29, v29
	v_mul_f32_e32 v20, v31, v31
	s_waitcnt vmcnt(1)
	v_mul_f32_e32 v21, v33, v33
	v_mul_f32_e32 v22, v35, v35
	v_fmac_f32_e32 v4, v28, v28
	v_fmac_f32_e32 v20, v30, v30
	v_fmac_f32_e32 v21, v32, v32
	v_fmac_f32_e32 v22, v34, v34
	v_add_f32_e32 v4, v4, v20
	v_add_f32_e32 v20, v21, v22
	v_add_f32_e32 v4, v4, v20
	v_add_f32_e32 v1, v1, v4
	ds_swizzle_b32 v4, v1 offset:swizzle(SWAP,1)
	v_cvt_pk_bf16_f32 v20, v28, v29
	v_cvt_pk_bf16_f32 v21, v30, v31
	v_cvt_pk_bf16_f32 v22, v32, v33
	v_cvt_pk_bf16_f32 v23, v34, v35
	s_waitcnt lgkmcnt(0)
	v_add_f32_e32 v1, v1, v4
	ds_swizzle_b32 v4, v1 offset:swizzle(SWAP,2)
	global_store_dwordx4 v[36:37], v[20:23], off offset:1024
	s_waitcnt lgkmcnt(0)
	v_add_f32_e32 v1, v1, v4
	ds_swizzle_b32 v4, v1 offset:swizzle(SWAP,4)
	s_waitcnt lgkmcnt(0)
	v_add_f32_e32 v1, v1, v4
	ds_swizzle_b32 v4, v1 offset:swizzle(SWAP,8)
	s_waitcnt lgkmcnt(0)
	v_add_f32_e32 v1, v1, v4
	ds_swizzle_b32 v4, v1 offset:swizzle(SWAP,16)
	s_waitcnt lgkmcnt(0)
	v_add_f32_e32 v1, v1, v4
	s_nop 0
	v_readlane_b32 s24, v1, 0
	v_readlane_b32 s25, v1, 32
	s_and_saveexec_b64 s[6:7], vcc
	s_cbranch_execz .LBB0_10
	v_mov_b32_e32 v1, s25
	v_lshl_add_u64 v[18:19], v[18:19], 2, s[62:63]
	v_add_f32_e32 v1, s24, v1
	global_store_dword v[18:19], v1, off
	s_branch .LBB0_10

.LBB0_1747:
	s_mul_hi_i32 s0, s8, 0x2aaaaaab
	s_lshr_b32 s1, s0, 31
	s_ashr_i32 s9, s0, 1
	s_add_i32 s9, s9, s1
	s_mul_i32 s0, s9, 12
	s_sub_i32 s0, s8, s0
	v_add_u32_e32 v4, s0, v1
	v_ashrrev_i32_e32 v5, 31, v4
	v_mad_i64_i32 v[84:85], s[18:19], s9, v234, v[4:5]
	s_mov_b64 s[18:19], 0x60
	v_lshlrev_b64 v[86:87], 3, v[84:85]
	v_lshl_add_u64 v[76:77], v[84:85], 0, s[18:19]
	v_lshl_add_u64 v[4:5], s[14:15], 0, v[86:87]
	v_lshlrev_b64 v[78:79], 3, v[76:77]
	s_barrier
	global_load_dword v22, v[4:5], off
	v_lshl_add_u64 v[4:5], s[14:15], 0, v[78:79]
	global_load_dword v90, v[4:5], off
	s_mov_b32 s1, 0xf149f2ca
	v_lshl_add_u64 v[86:87], s[6:7], 0, v[86:87]
	s_mov_b64 s[18:19], 0xc0
	v_lshl_add_u64 v[72:73], v[84:85], 0, s[18:19]
	v_lshl_add_u64 v[78:79], s[6:7], 0, v[78:79]
	v_lshlrev_b64 v[74:75], 3, v[72:73]
	v_lshl_add_u64 v[4:5], s[14:15], 0, v[74:75]
	s_mov_b64 s[18:19], 0x120
	v_lshl_add_u64 v[74:75], s[6:7], 0, v[74:75]
	v_lshl_add_u64 v[68:69], v[84:85], 0, s[18:19]
	v_lshlrev_b64 v[70:71], 3, v[68:69]
	global_load_dword v91, v[4:5], off
	s_mov_b64 s[18:19], 0x180
	v_lshl_add_u64 v[64:65], v[84:85], 0, s[18:19]
	v_lshlrev_b64 v[66:67], 3, v[64:65]
	s_mov_b64 s[18:19], 0x1e0
	v_lshl_add_u64 v[60:61], v[84:85], 0, s[18:19]
	v_lshlrev_b64 v[62:63], 3, v[60:61]
	s_mov_b64 s[18:19], 0x240
	v_lshl_add_u64 v[56:57], v[84:85], 0, s[18:19]
	s_mov_b64 s[18:19], 0x2a0
	v_lshlrev_b64 v[58:59], 3, v[56:57]
	v_lshl_add_u64 v[52:53], v[84:85], 0, s[18:19]
	s_mov_b64 s[18:19], 0x300
	v_lshlrev_b64 v[54:55], 3, v[52:53]
	v_lshl_add_u64 v[48:49], v[84:85], 0, s[18:19]
	s_mov_b64 s[18:19], 0x360
	v_lshlrev_b64 v[50:51], 3, v[48:49]
	v_lshl_add_u64 v[44:45], v[84:85], 0, s[18:19]
	s_mov_b64 s[18:19], 0x3c0
	v_lshlrev_b64 v[46:47], 3, v[44:45]
	v_lshl_add_u64 v[40:41], v[84:85], 0, s[18:19]
	s_mov_b64 s[18:19], 0x420
	v_lshlrev_b64 v[42:43], 3, v[40:41]
	v_lshl_add_u64 v[36:37], v[84:85], 0, s[18:19]
	s_mov_b64 s[18:19], 0x480
	v_lshlrev_b64 v[38:39], 3, v[36:37]
	v_lshl_add_u64 v[32:33], v[84:85], 0, s[18:19]
	s_mov_b64 s[18:19], 0x4e0
	v_lshlrev_b64 v[34:35], 3, v[32:33]
	v_lshl_add_u64 v[28:29], v[84:85], 0, s[18:19]
	v_lshlrev_b64 v[30:31], 3, v[28:29]
	s_mov_b64 s[18:19], 0x540
	v_lshl_add_u64 v[24:25], v[84:85], 0, s[18:19]
	v_lshlrev_b64 v[26:27], 3, v[24:25]
	s_mov_b64 s[18:19], 0x5a0
	v_lshlrev_b64 v[76:77], 10, v[76:77]
	v_lshl_add_u64 v[76:77], v[16:17], 0, v[76:77]
	v_lshlrev_b64 v[72:73], 10, v[72:73]
	v_lshl_add_u64 v[72:73], v[16:17], 0, v[72:73]
	v_lshlrev_b64 v[68:69], 10, v[68:69]
	v_lshl_add_u64 v[68:69], v[16:17], 0, v[68:69]
	v_lshlrev_b64 v[64:65], 10, v[64:65]
	v_lshl_add_u64 v[64:65], v[16:17], 0, v[64:65]
	v_lshlrev_b64 v[60:61], 10, v[60:61]
	v_lshl_add_u64 v[60:61], v[16:17], 0, v[60:61]
	v_lshlrev_b64 v[56:57], 10, v[56:57]
	v_lshl_add_u64 v[56:57], v[16:17], 0, v[56:57]
	v_lshlrev_b64 v[52:53], 10, v[52:53]
	v_lshl_add_u64 v[52:53], v[16:17], 0, v[52:53]
	v_lshlrev_b64 v[48:49], 10, v[48:49]
	v_lshl_add_u64 v[48:49], v[16:17], 0, v[48:49]
	v_lshlrev_b64 v[44:45], 10, v[44:45]
	v_lshl_add_u64 v[44:45], v[16:17], 0, v[44:45]
	v_lshlrev_b64 v[40:41], 10, v[40:41]
	v_lshl_add_u64 v[40:41], v[16:17], 0, v[40:41]
	v_lshlrev_b64 v[36:37], 10, v[36:37]
	v_lshl_add_u64 v[36:37], v[16:17], 0, v[36:37]
	v_lshlrev_b64 v[32:33], 10, v[32:33]
	v_lshl_add_u64 v[32:33], v[16:17], 0, v[32:33]
	v_lshlrev_b64 v[28:29], 10, v[28:29]
	v_lshl_add_u64 v[28:29], v[16:17], 0, v[28:29]
	v_lshlrev_b64 v[24:25], 10, v[24:25]
	v_lshl_add_u64 v[24:25], v[16:17], 0, v[24:25]
	s_lshl_b32 s0, s0, 6
	s_waitcnt vmcnt(1)
	v_max3_f32 v6, v22, s1, v90
	s_mov_b32 s1, 0x34cd0000
	v_add_co_u32_e32 v86, vcc, s1, v86
	s_nop 1
	v_addc_co_u32_e32 v87, vcc, 0, v87, vcc
	v_add_co_u32_e32 v78, vcc, s1, v78
	global_load_dword v86, v[86:87], off offset:4
	s_nop 0
	v_addc_co_u32_e32 v79, vcc, 0, v79, vcc
	v_add_co_u32_e32 v74, vcc, s1, v74
	global_load_dword v78, v[78:79], off offset:4
	s_nop 0
	v_addc_co_u32_e32 v75, vcc, 0, v75, vcc
	global_load_dword v74, v[74:75], off offset:4
	v_lshl_add_u64 v[4:5], s[14:15], 0, v[70:71]
	v_lshl_add_u64 v[70:71], s[6:7], 0, v[70:71]
	v_add_co_u32_e32 v70, vcc, s1, v70
	global_load_dword v92, v[4:5], off
	s_nop 0
	v_addc_co_u32_e32 v71, vcc, 0, v71, vcc
	global_load_dword v70, v[70:71], off offset:4
	v_lshl_add_u64 v[4:5], s[14:15], 0, v[66:67]
	v_lshl_add_u64 v[66:67], s[6:7], 0, v[66:67]
	v_add_co_u32_e32 v66, vcc, s1, v66
	global_load_dword v93, v[4:5], off
	s_nop 0
	v_addc_co_u32_e32 v67, vcc, 0, v67, vcc
	global_load_dword v66, v[66:67], off offset:4
	v_lshl_add_u64 v[4:5], s[14:15], 0, v[62:63]
	v_lshl_add_u64 v[62:63], s[6:7], 0, v[62:63]
	v_add_co_u32_e32 v62, vcc, s1, v62
	global_load_dword v94, v[4:5], off
	s_nop 0
	v_addc_co_u32_e32 v63, vcc, 0, v63, vcc
	global_load_dword v62, v[62:63], off offset:4
	v_lshl_add_u64 v[4:5], s[14:15], 0, v[58:59]
	global_load_dword v95, v[4:5], off
	v_lshl_add_u64 v[4:5], s[14:15], 0, v[54:55]
	global_load_dword v96, v[4:5], off
	v_lshl_add_u64 v[4:5], s[14:15], 0, v[50:51]
	global_load_dword v97, v[4:5], off
	v_lshl_add_u64 v[4:5], s[14:15], 0, v[46:47]
	global_load_dword v83, v[4:5], off
	v_lshl_add_u64 v[4:5], s[14:15], 0, v[42:43]
	global_load_dword v82, v[4:5], off
	v_lshl_add_u64 v[4:5], s[14:15], 0, v[38:39]
	global_load_dword v81, v[4:5], off
	v_lshl_add_u64 v[4:5], s[14:15], 0, v[34:35]
	global_load_dword v80, v[4:5], off
	v_lshl_add_u64 v[4:5], s[14:15], 0, v[30:31]
	global_load_dword v23, v[4:5], off
	v_lshl_add_u64 v[4:5], s[14:15], 0, v[26:27]
	global_load_dword v21, v[4:5], off
	v_lshl_add_u64 v[4:5], v[84:85], 0, s[18:19]
	v_lshlrev_b64 v[84:85], 10, v[84:85]
	v_lshl_add_u64 v[84:85], v[16:17], 0, v[84:85]
	v_lshl_add_u64 v[58:59], s[6:7], 0, v[58:59]
	v_add_co_u32_e32 v58, vcc, s1, v58
	v_lshl_add_u64 v[54:55], s[6:7], 0, v[54:55]
	s_nop 0
	v_addc_co_u32_e32 v59, vcc, 0, v59, vcc
	v_add_co_u32_e32 v54, vcc, s1, v54
	v_lshl_add_u64 v[50:51], s[6:7], 0, v[50:51]
	s_nop 0
	v_addc_co_u32_e32 v55, vcc, 0, v55, vcc
	v_add_co_u32_e32 v50, vcc, s1, v50
	v_lshl_add_u64 v[46:47], s[6:7], 0, v[46:47]
	s_nop 0
	v_addc_co_u32_e32 v51, vcc, 0, v51, vcc
	v_add_co_u32_e32 v46, vcc, s1, v46
	v_lshl_add_u64 v[42:43], s[6:7], 0, v[42:43]
	s_nop 0
	v_addc_co_u32_e32 v47, vcc, 0, v47, vcc
	v_add_co_u32_e32 v42, vcc, s1, v42
	v_lshl_add_u64 v[38:39], s[6:7], 0, v[38:39]
	s_nop 0
	v_addc_co_u32_e32 v43, vcc, 0, v43, vcc
	v_add_co_u32_e32 v38, vcc, s1, v38
	v_lshl_add_u64 v[34:35], s[6:7], 0, v[34:35]
	s_nop 0
	v_addc_co_u32_e32 v39, vcc, 0, v39, vcc
	v_add_co_u32_e32 v34, vcc, s1, v34
	v_lshl_add_u64 v[30:31], s[6:7], 0, v[30:31]
	s_nop 0
	v_addc_co_u32_e32 v35, vcc, 0, v35, vcc
	v_add_co_u32_e32 v30, vcc, s1, v30
	v_lshl_add_u64 v[26:27], s[6:7], 0, v[26:27]
	s_waitcnt vmcnt(14)
	v_max3_f32 v6, v6, v91, v92
	v_addc_co_u32_e32 v31, vcc, 0, v31, vcc
	v_add_co_u32_e32 v26, vcc, s1, v26
	s_waitcnt vmcnt(10)
	v_max3_f32 v6, v6, v93, v94
	v_addc_co_u32_e32 v27, vcc, 0, v27, vcc
	s_waitcnt vmcnt(7)
	v_max3_f32 v6, v6, v95, v96
	s_waitcnt vmcnt(5)
	v_max3_f32 v6, v6, v97, v83
	s_waitcnt vmcnt(3)
	v_max3_f32 v6, v6, v82, v81
	s_waitcnt vmcnt(1)
	v_max3_f32 v13, v6, v80, v23
	v_lshlrev_b64 v[6:7], 3, v[4:5]
	v_lshl_add_u64 v[88:89], s[14:15], 0, v[6:7]
	global_load_dword v11, v[88:89], off
	v_lshl_add_u64 v[6:7], s[6:7], 0, v[6:7]
	v_add_co_u32_e32 v6, vcc, s1, v6
	v_lshlrev_b64 v[4:5], 10, v[4:5]
	s_nop 0
	v_addc_co_u32_e32 v7, vcc, 0, v7, vcc
	v_lshl_add_u64 v[4:5], v[16:17], 0, v[4:5]
	s_ashr_i32 s1, s0, 31
	s_waitcnt vmcnt(0)
	v_max3_f32 v13, v13, v21, v11
	v_sub_f32_e32 v22, v22, v13
	v_exp_f32_e32 v88, v22
	v_sub_f32_e32 v23, v23, v13
	v_sub_f32_e32 v21, v21, v13
	v_sub_f32_e32 v11, v11, v13
	v_fma_f32 v89, v86, v88, 0
	global_load_dwordx4 v[84:87], v[84:85], off
	global_load_dwordx4 v[162:165], v[76:77], off
	global_load_dwordx4 v[166:169], v[72:73], off
	global_load_dwordx4 v[170:173], v[68:69], off
	global_load_dwordx4 v[174:177], v[64:65], off
	global_load_dwordx4 v[178:181], v[60:61], off
	global_load_dwordx4 v[182:185], v[56:57], off
	global_load_dwordx4 v[186:189], v[52:53], off
	global_load_dwordx4 v[190:193], v[48:49], off
	global_load_dwordx4 v[194:197], v[44:45], off
	global_load_dwordx4 v[204:207], v[40:41], off
	global_load_dwordx4 v[210:213], v[36:37], off
	global_load_dwordx4 v[214:217], v[32:33], off
	global_load_dwordx4 v[218:221], v[28:29], off
	global_load_dwordx4 v[222:225], v[24:25], off
	global_load_dwordx4 v[226:229], v[4:5], off
	global_load_dword v248, v[58:59], off offset:4
	global_load_dword v249, v[54:55], off offset:4
	global_load_dword v250, v[50:51], off offset:4
	global_load_dword v251, v[46:47], off offset:4
	global_load_dword v232, v[42:43], off offset:4
	global_load_dword v233, v[38:39], off offset:4
	global_load_dword v198, v[34:35], off offset:4
	global_load_dword v199, v[30:31], off offset:4
	global_load_dword v244, v[26:27], off offset:4
	global_load_dword v245, v[6:7], off offset:4
	v_mov_b32_e32 v22, 0
	s_waitcnt vmcnt(0)
	v_pk_fma_f32 v[86:87], v[86:87], v[88:89], 0 op_sel_hi:[1,0,0]
	v_pk_fma_f32 v[84:85], v[84:85], v[88:89], 0 op_sel_hi:[1,0,0]
	v_sub_f32_e32 v88, v90, v13
	v_exp_f32_e32 v88, v88
	s_nop 0
	v_fmac_f32_e32 v89, v88, v78
	s_nop 0
	v_pk_fma_f32 v[76:77], v[162:163], v[88:89], v[84:85] op_sel_hi:[1,0,1]
	v_sub_f32_e32 v84, v91, v13
	v_exp_f32_e32 v84, v84
	v_pk_fma_f32 v[78:79], v[164:165], v[88:89], v[86:87] op_sel_hi:[1,0,1]
	v_fmac_f32_e32 v89, v84, v74
	s_nop 0
	v_pk_fma_f32 v[72:73], v[84:85], v[166:167], v[76:77] op_sel_hi:[0,1,1]
	v_sub_f32_e32 v76, v92, v13
	v_exp_f32_e32 v76, v76
	v_pk_fma_f32 v[74:75], v[84:85], v[168:169], v[78:79] op_sel_hi:[0,1,1]
	v_fmac_f32_e32 v89, v76, v70
	s_nop 0
	v_pk_fma_f32 v[68:69], v[76:77], v[170:171], v[72:73] op_sel_hi:[0,1,1]
	v_sub_f32_e32 v72, v93, v13
	v_exp_f32_e32 v72, v72
	v_pk_fma_f32 v[70:71], v[76:77], v[172:173], v[74:75] op_sel_hi:[0,1,1]
	v_fmac_f32_e32 v89, v72, v66
	s_nop 0
	v_pk_fma_f32 v[64:65], v[72:73], v[174:175], v[68:69] op_sel_hi:[0,1,1]
	v_sub_f32_e32 v68, v94, v13
	v_exp_f32_e32 v68, v68
	v_pk_fma_f32 v[66:67], v[72:73], v[176:177], v[70:71] op_sel_hi:[0,1,1]
	v_fmac_f32_e32 v89, v68, v62
	s_nop 0
	v_pk_fma_f32 v[62:63], v[68:69], v[180:181], v[66:67] op_sel_hi:[0,1,1]
	v_pk_fma_f32 v[60:61], v[68:69], v[178:179], v[64:65] op_sel_hi:[0,1,1]
	v_sub_f32_e32 v64, v95, v13
	v_exp_f32_e32 v64, v64
	s_nop 0
	v_pk_fma_f32 v[56:57], v[64:65], v[182:183], v[60:61] op_sel_hi:[0,1,1]
	v_sub_f32_e32 v60, v96, v13
	v_pk_fma_f32 v[58:59], v[64:65], v[184:185], v[62:63] op_sel_hi:[0,1,1]
	v_exp_f32_e32 v65, v60
	s_nop 0
	v_pk_mul_f32 v[54:55], v[64:65], v[248:249]
	s_nop 0
	v_add_f32_e32 v54, v89, v54
	v_add_f32_e32 v61, v54, v55
	v_mov_b32_e32 v60, v65
	s_nop 0
	v_pk_fma_f32 v[54:55], v[60:61], v[188:189], v[58:59] op_sel_hi:[0,1,1]
	v_pk_fma_f32 v[52:53], v[60:61], v[186:187], v[56:57] op_sel_hi:[0,1,1]
	v_sub_f32_e32 v56, v97, v13
	v_exp_f32_e32 v56, v56
	s_nop 0
	v_pk_fma_f32 v[48:49], v[56:57], v[190:191], v[52:53] op_sel_hi:[0,1,1]
	v_sub_f32_e32 v52, v83, v13
	v_pk_fma_f32 v[50:51], v[56:57], v[192:193], v[54:55] op_sel_hi:[0,1,1]
	v_exp_f32_e32 v57, v52
	s_nop 0
	v_pk_mul_f32 v[46:47], v[56:57], v[250:251]
	s_nop 0
	v_add_f32_e32 v46, v61, v46
	v_add_f32_e32 v53, v46, v47
	v_mov_b32_e32 v52, v57
	s_nop 0
	v_pk_fma_f32 v[46:47], v[52:53], v[196:197], v[50:51] op_sel_hi:[0,1,1]
	v_pk_fma_f32 v[44:45], v[52:53], v[194:195], v[48:49] op_sel_hi:[0,1,1]
	v_sub_f32_e32 v48, v82, v13
	v_exp_f32_e32 v48, v48
	s_nop 0
	v_pk_fma_f32 v[40:41], v[48:49], v[204:205], v[44:45] op_sel_hi:[0,1,1]
	v_sub_f32_e32 v44, v81, v13
	v_pk_fma_f32 v[42:43], v[48:49], v[206:207], v[46:47] op_sel_hi:[0,1,1]
	v_exp_f32_e32 v49, v44
	s_nop 0
	v_pk_mul_f32 v[38:39], v[48:49], v[232:233]
	s_nop 0
	v_add_f32_e32 v38, v53, v38
	v_add_f32_e32 v45, v38, v39
	v_mov_b32_e32 v44, v49
	s_nop 0
	v_pk_fma_f32 v[38:39], v[44:45], v[212:213], v[42:43] op_sel_hi:[0,1,1]
	v_pk_fma_f32 v[36:37], v[44:45], v[210:211], v[40:41] op_sel_hi:[0,1,1]
	v_sub_f32_e32 v40, v80, v13
	v_exp_f32_e32 v40, v40
	s_nop 0
	v_pk_fma_f32 v[34:35], v[40:41], v[216:217], v[38:39] op_sel_hi:[0,1,1]
	v_pk_fma_f32 v[32:33], v[40:41], v[214:215], v[36:37] op_sel_hi:[0,1,1]
	v_exp_f32_e32 v41, v23
	s_nop 0
	v_pk_mul_f32 v[30:31], v[40:41], v[198:199]
	s_nop 0
	v_add_f32_e32 v23, v45, v30
	v_add_f32_e32 v23, v23, v31
	v_mov_b32_e32 v36, v41
	s_nop 0
	v_pk_fma_f32 v[30:31], v[36:37], v[220:221], v[34:35] op_sel_hi:[0,1,1]
	v_pk_fma_f32 v[28:29], v[36:37], v[218:219], v[32:33] op_sel_hi:[0,1,1]
	v_exp_f32_e32 v32, v21
	s_nop 0
	v_pk_fma_f32 v[26:27], v[32:33], v[224:225], v[30:31] op_sel_hi:[0,1,1]
	v_pk_fma_f32 v[24:25], v[32:33], v[222:223], v[28:29] op_sel_hi:[0,1,1]
	v_exp_f32_e32 v33, v11
	v_mov_b32_e32 v30, v22
	v_mov_b32_e32 v31, v22
	v_pk_mul_f32 v[6:7], v[32:33], v[244:245]
	s_nop 0
	v_add_f32_e32 v6, v23, v6
	v_add_f32_e32 v11, v6, v7
	v_div_scale_f32 v13, s[18:19], v11, v11, 1.0
	v_rcp_f32_e32 v21, v13
	v_mov_b32_e32 v28, v33
	s_mov_b32 s18, -4
	v_fma_f32 v23, -v13, v21, 1.0
	v_fmac_f32_e32 v21, v23, v21
	v_div_scale_f32 v23, vcc, 1.0, v11, 1.0
	s_nop 0
	v_pk_fma_f32 v[4:5], v[28:29], v[226:227], v[24:25] op_sel_hi:[0,1,1]
	v_mul_f32_e32 v24, v23, v21
	v_fma_f32 v25, -v13, v24, v23
	v_fmac_f32_e32 v24, v25, v21
	v_fma_f32 v13, -v13, v24, v23
	v_div_fmas_f32 v13, v13, v21, v24
	v_pk_fma_f32 v[6:7], v[28:29], v[228:229], v[26:27] op_sel_hi:[0,1,1]
	v_div_fixup_f32 v24, v13, v11, 1.0
	v_pk_mul_f32 v[6:7], v[6:7], v[24:25] op_sel_hi:[1,0]
	v_pk_mul_f32 v[4:5], v[4:5], v[24:25] op_sel_hi:[1,0]
	v_add_u32_e32 v11, v8, v10
	ds_write_b128 v11, v[4:7]
	v_lshl_add_u64 v[24:25], s[0:1], 2, v[18:19]
	v_mov_b32_e32 v11, v12
	v_mov_b32_e32 v23, v22
	v_mov_b32_e32 v26, v22
	v_mov_b32_e32 v27, v22
	v_mov_b32_e32 v28, v22
	v_mov_b32_e32 v29, v22
	s_waitcnt lgkmcnt(0)
	s_barrier
